# QK^T read burst plus static s_setprio 1 for the older wave half (waves 0-3) during attention, reset before the conv branch
# speedup vs baseline: 1.0051x; 1.0051x over previous
; #define LAS __attribute__((address_space(3)))
; __device__ __forceinline__ void unit(const Ctx& C, int xq, int idx, LAS unsigned char* lds) {
;     ...
;     const int pi = 16 * (q >> 4) + 8 * ((q >> 2) & 1) + 4 * ((q >> 3) & 1) + (q & 3);
;     const int koff = mp * KSL + pi * 144 + hi * 16;
;     const int voff = KBUF + q * 144 + hi * 16;
;     const LAS float* tab = (const LAS float*)(lds + TAB_OFF) + h * 256;
;     const float b15 = tab[0];
; __global__ void __launch_bounds__(512, 2) mk_fwd(Args a) {
;     ...
;         float d1 = 0.f, d2 = 0.f;
;         for (int i = 0; i < 64; ++i) { d1 += a.in[I_LQ1][i] * a.in[I_LK1][i]; d2 += a.in[I_LQ2][i] * a.in[I_LK2][i]; }
;         att::Ctx C{PROJ, KC, VTC, VTP, VTN, OOB, a.in[I_SUB], __expf(d1) - __expf(d2) + 0.2f};
;         LAS int* misc = (LAS int*)(lds + MISC_OFF);
;         __syncthreads();
.LBB0_475:
	s_add_u32 s4, s54, s0
	s_addc_u32 s5, s55, s1
	global_load_dwordx4 v[4:7], v2, s[4:5]
	global_load_dwordx4 v[8:11], v2, s[4:5] offset:16
	s_add_u32 s4, s56, s0
	s_addc_u32 s5, s57, s1
	global_load_dwordx4 v[12:15], v2, s[4:5]
	global_load_dwordx4 v[16:19], v2, s[4:5] offset:16
	s_add_u32 s4, s58, s0
	s_addc_u32 s5, s59, s1
	global_load_dwordx4 v[20:23], v2, s[4:5]
	global_load_dwordx4 v[24:27], v2, s[4:5] offset:16
	s_add_u32 s4, s60, s0
	s_addc_u32 s5, s61, s1
	global_load_dwordx4 v[28:31], v2, s[4:5]
	global_load_dwordx4 v[32:35], v2, s[4:5] offset:16
	s_add_u32 s0, s0, 32
	s_addc_u32 s1, s1, 0
	s_cmpk_eq_i32 s0, 0x100
	s_waitcnt vmcnt(7)
	v_mov_b32_e32 v36, v4
	v_mov_b32_e32 v4, v6
	s_waitcnt vmcnt(6)
	v_mov_b32_e32 v6, v8
	v_mov_b32_e32 v8, v10
	s_waitcnt vmcnt(5)
	v_mov_b32_e32 v10, v12
	v_mov_b32_e32 v12, v14
	s_waitcnt vmcnt(3)
	v_mov_b32_e32 v37, v20
	v_mov_b32_e32 v20, v5
	v_mov_b32_e32 v5, v22
	v_mov_b32_e32 v22, v7
	s_waitcnt vmcnt(2)
	v_mov_b32_e32 v7, v24
	v_mov_b32_e32 v24, v9
	v_mov_b32_e32 v9, v26
	v_mov_b32_e32 v26, v11
	s_waitcnt vmcnt(1)
	v_mov_b32_e32 v11, v28
	v_mov_b32_e32 v28, v13
	v_pk_fma_f32 v[0:1], v[36:37], v[10:11], v[0:1]
	v_mov_b32_e32 v13, v30
	v_pk_fma_f32 v[0:1], v[20:21], v[28:29], v[0:1]
	v_mov_b32_e32 v30, v15
	v_pk_fma_f32 v[0:1], v[4:5], v[12:13], v[0:1]
	v_mov_b32_e32 v14, v16
	s_waitcnt vmcnt(0)
	v_mov_b32_e32 v15, v32
	v_pk_fma_f32 v[0:1], v[22:23], v[30:31], v[0:1]
	v_mov_b32_e32 v32, v17
	v_pk_fma_f32 v[0:1], v[6:7], v[14:15], v[0:1]
	v_mov_b32_e32 v16, v18
	v_mov_b32_e32 v17, v34
	v_pk_fma_f32 v[0:1], v[24:25], v[32:33], v[0:1]
	v_mov_b32_e32 v34, v19
	v_pk_fma_f32 v[0:1], v[8:9], v[16:17], v[0:1]
	s_nop 0
	v_pk_fma_f32 v[0:1], v[26:27], v[34:35], v[0:1]
	s_cbranch_scc0 .LBB0_475
	v_mul_f32_e32 v0, 0x3fb8aa3b, v0
	v_mul_f32_e32 v1, 0x3fb8aa3b, v1
	v_exp_f32_e32 v0, v0
	v_exp_f32_e32 v1, v1
	v_lshlrev_b32_e32 v2, 4, v179
	v_and_b32_e32 v2, 0x70, v2
	v_add_u32_e32 v3, 0, v2
	v_lshlrev_b32_e32 v2, 1, v179
	v_lshrrev_b32_e32 v8, 1, v179
	v_sub_f32_e32 v0, v0, v1
	v_add_u32_e32 v1, 0x200, v179
	v_and_b32_e32 v2, 8, v2
	v_and_b32_e32 v8, 4, v8
	v_and_b32_e32 v9, 19, v179
	v_lshrrev_b32_e32 v204, 4, v1
	v_lshrrev_b32_e32 v205, 3, v1
	v_bfe_i32 v1, v179, 3, 1
	s_movk_i32 s0, 0x90
	v_or3_b32 v2, v9, v2, v8
	v_lshlrev_b32_e32 v184, 4, v178
	s_add_u32 s9, s68, 0x1ab00200
	v_lshrrev_b32_e32 v177, 4, v179
	v_lshrrev_b32_e32 v203, 3, v179
	v_and_b32_e32 v1, 0x2400, v1
	v_mad_u32_u24 v206, v2, s0, v184
	v_mul_u32_u24_e32 v2, 0x90, v201
	s_addc_u32 s72, s69, 0
	v_add_f32_e32 v182, 0x3e4ccccd, v0
	v_lshlrev_b32_e32 v0, 3, v178
	v_mov_b32_e32 v185, 0
	v_add_u32_e32 v1, v3, v1
	v_mul_u32_u24_e32 v4, 0x90, v177
	v_mul_u32_u24_e32 v5, 0x90, v203
	v_mul_u32_u24_e32 v6, 0x90, v204
	v_mul_u32_u24_e32 v7, 0x90, v205
	v_add3_u32 v207, v2, v184, 0
	v_lshlrev_b32_e32 v2, 2, v178
	s_add_u32 s73, s68, 0x3d80800
	v_and_b32_e32 v186, 0x78, v221
	s_mov_b32 s5, 0
	v_add_u32_e32 v208, 0xd800, v207
	v_lshlrev_b32_e32 v209, 9, v178
	v_lshl_add_u64 v[188:189], s[62:63], 0, v[184:185]
	v_mov_b32_e32 v183, v182
	v_sub_u32_e32 v210, v0, v201
	s_addc_u32 s76, s69, 0
	s_add_i32 s77, 0, 0x26000
	v_lshlrev_b32_e32 v190, 1, v0
	s_add_i32 s78, 0, 0x242fc
	s_mov_b32 s8, 0x3e38aa3b
	v_lshlrev_b32_e32 v192, 1, v2
	v_mov_b32_e32 v211, 0x358637bd
	v_add_u32_e32 v212, v1, v4
	v_add_u32_e32 v213, v3, v5
	v_add_u32_e32 v214, v1, v6
	v_add_u32_e32 v215, v3, v7
	s_mov_b32 s79, 0
	s_waitcnt lgkmcnt(0)
	s_barrier
	v_readfirstlane_b32 s0, v179
	s_nop 3
	s_cmp_lt_u32 s0, 0x100
	s_cbranch_scc0 .Lp2_prio_done
	s_setprio 1
